# 3-slot K/V ring in attention (LDS-DMA two tiles ahead) with the threshold-8 rescale
# baseline (speedup 1.0000x reference)
.Latt_loop:
	s_waitcnt vmcnt(6)
	s_barrier
	ds_read_b128 v[64:67], v173 offset:24576
	ds_read_b128 v[68:71], v173 offset:28672
	s_mov_b32 m0, s44
	ds_read_b128 v[72:75], v171 offset:24576
	global_load_lds_dwordx4 v200, s[40:41]
	s_add_u32 m0, s44, 0x400
	ds_read_b128 v[76:79], v171 offset:28672
	global_load_lds_dwordx4 v190, s[40:41]
	s_mov_b32 m0, s45
	ds_read_b128 v[216:219], v169 offset:24576
	global_load_lds_dwordx4 v192, s[42:43]
	s_add_u32 m0, s45, 0x400
	ds_read_b128 v[220:223], v169 offset:28672
	global_load_lds_dwordx4 v194, s[42:43]
	s_add_u32 m0, s45, 0x800
	ds_read_b128 v[224:227], v167 offset:24576
	global_load_lds_dwordx4 v196, s[42:43]
	s_add_u32 m0, s45, 0xc00
	ds_read_b128 v[228:231], v167 offset:28672
	global_load_lds_dwordx4 v198, s[42:43]
	s_add_u32 s40, s40, 0x18000
	s_addc_u32 s41, s41, 0
	s_add_u32 s42, s42, 0x80
	s_addc_u32 s43, s43, 0
	ds_read_b128 v[232:235], v173 offset:32768
	ds_read_b128 v[236:239], v173 offset:36864
	ds_read_b128 v[240:243], v173 offset:40960
	ds_read_b128 v[244:247], v173 offset:45056
	s_waitcnt lgkmcnt(11)
	v_mfma_f32_32x32x16_bf16 v[112:127], v[64:67], v[140:143], v[96:111]
	ds_read_b128 v[64:67], v171 offset:32768
	s_waitcnt lgkmcnt(11)
	v_mfma_f32_32x32x16_bf16 v[80:95], v[68:71], v[140:143], v[96:111]
	ds_read_b128 v[68:71], v171 offset:36864
	s_waitcnt lgkmcnt(11)
	v_mfma_f32_32x32x16_bf16 v[112:127], v[72:75], v[136:139], v[112:127]
	ds_read_b128 v[72:75], v171 offset:40960
	s_waitcnt lgkmcnt(11)
	v_mfma_f32_32x32x16_bf16 v[80:95], v[76:79], v[136:139], v[80:95]
	ds_read_b128 v[76:79], v171 offset:45056
	s_waitcnt lgkmcnt(11)
	v_mfma_f32_32x32x16_bf16 v[112:127], v[216:219], v[132:135], v[112:127]
	ds_read_b128 v[216:219], v169 offset:32768
	s_waitcnt lgkmcnt(11)
	v_mfma_f32_32x32x16_bf16 v[80:95], v[220:223], v[132:135], v[80:95]
	ds_read_b128 v[220:223], v169 offset:36864
	s_waitcnt lgkmcnt(11)
	v_mfma_f32_32x32x16_bf16 v[112:127], v[224:227], v[128:131], v[112:127]
	ds_read_b128 v[224:227], v169 offset:40960
	s_waitcnt lgkmcnt(11)
	v_mfma_f32_32x32x16_bf16 v[80:95], v[228:231], v[128:131], v[80:95]
	ds_read_b128 v[228:231], v169 offset:45056
	s_nop 7
	s_nop 3
	v_max3_f32 v175, v112, v113, v114
	v_max3_f32 v177, v115, v116, v117
	v_max3_f32 v179, v118, v119, v120
	v_max3_f32 v181, v121, v122, v123
	v_max3_f32 v248, v124, v125, v126
	v_max3_f32 v249, v127, v80, v81
	v_max3_f32 v250, v82, v83, v84
	v_max3_f32 v251, v85, v86, v87
	v_max3_f32 v253, v88, v89, v90
	v_max3_f32 v254, v91, v92, v93
	v_max_f32_e32 v255, v94, v95
	v_max3_f32 v175, v175, v177, v179
	v_max3_f32 v181, v181, v248, v249
	v_max3_f32 v250, v250, v251, v253
	v_max_f32_e32 v254, v254, v255
	v_max3_f32 v175, v175, v181, v250
	v_max_f32_e32 v175, v175, v254
	v_mov_b32_e32 v177, v175
	s_nop 1
	v_permlane32_swap_b32_e32 v175, v177
	v_max_f32_e32 v175, v175, v177
	v_cmp_lt_f32_e32 vcc, 0x41000000, v175
	s_cbranch_vccnz .Latt_resc_a
.Latt_cont_a:
	v_exp_f32_e32 v112, v112
	v_exp_f32_e32 v113, v113
	v_exp_f32_e32 v114, v114
	v_exp_f32_e32 v115, v115
	v_exp_f32_e32 v116, v116
	v_exp_f32_e32 v117, v117
	v_exp_f32_e32 v118, v118
	v_exp_f32_e32 v119, v119
	v_add_f32_e32 v183, v112, v113
	v_add_f32_e32 v183, v183, v114
	v_add_f32_e32 v183, v183, v115
	v_add_f32_e32 v183, v183, v116
	v_add_f32_e32 v183, v183, v117
	v_add_f32_e32 v183, v183, v118
	v_add_f32_e32 v183, v183, v119
	v_cvt_pk_bf16_f32 v112, v112, v113
	v_cvt_pk_bf16_f32 v113, v114, v115
	v_cvt_pk_bf16_f32 v114, v116, v117
	v_cvt_pk_bf16_f32 v115, v118, v119
	v_exp_f32_e32 v120, v120
	v_exp_f32_e32 v121, v121
	s_waitcnt lgkmcnt(8)
	v_mfma_f32_32x32x16_bf16 v[48:63], v[232:235], v[112:115], v[48:63]
	v_exp_f32_e32 v122, v122
	v_exp_f32_e32 v123, v123
	v_exp_f32_e32 v124, v124
	v_mfma_f32_32x32x16_bf16 v[32:47], v[236:239], v[112:115], v[32:47]
	v_exp_f32_e32 v125, v125
	v_exp_f32_e32 v126, v126
	v_exp_f32_e32 v127, v127
	v_mfma_f32_32x32x16_bf16 v[16:31], v[240:243], v[112:115], v[16:31]
	v_add_f32_e32 v185, v120, v121
	v_add_f32_e32 v185, v185, v122
	v_add_f32_e32 v185, v185, v123
	v_add_f32_e32 v185, v185, v124
	v_add_f32_e32 v185, v185, v125
	v_add_f32_e32 v185, v185, v126
	v_mfma_f32_32x32x16_bf16 v[0:15], v[244:247], v[112:115], v[0:15]
	ds_read_b128 v[232:235], v167 offset:32768
	ds_read_b128 v[236:239], v167 offset:36864
	ds_read_b128 v[240:243], v167 offset:40960
	ds_read_b128 v[244:247], v167 offset:45056
	v_add_f32_e32 v185, v185, v127
	v_cvt_pk_bf16_f32 v116, v120, v121
	v_cvt_pk_bf16_f32 v117, v122, v123
	v_cvt_pk_bf16_f32 v118, v124, v125
	v_cvt_pk_bf16_f32 v119, v126, v127
	s_nop 0
	s_waitcnt lgkmcnt(8)
	v_mfma_f32_32x32x16_bf16 v[48:63], v[64:67], v[116:119], v[48:63]
	v_exp_f32_e32 v80, v80
	v_exp_f32_e32 v81, v81
	v_exp_f32_e32 v82, v82
	v_mfma_f32_32x32x16_bf16 v[32:47], v[68:71], v[116:119], v[32:47]
	v_exp_f32_e32 v83, v83
	v_exp_f32_e32 v84, v84
	v_exp_f32_e32 v85, v85
	v_mfma_f32_32x32x16_bf16 v[16:31], v[72:75], v[116:119], v[16:31]
	v_exp_f32_e32 v86, v86
	v_exp_f32_e32 v87, v87
	v_add_f32_e32 v187, v80, v81
	v_add_f32_e32 v187, v187, v82
	v_mfma_f32_32x32x16_bf16 v[0:15], v[76:79], v[116:119], v[0:15]
	v_add_f32_e32 v187, v187, v83
	v_add_f32_e32 v187, v187, v84
	v_add_f32_e32 v187, v187, v85
	v_add_f32_e32 v187, v187, v86
	v_add_f32_e32 v187, v187, v87
	v_cvt_pk_bf16_f32 v80, v80, v81
	v_cvt_pk_bf16_f32 v81, v82, v83
	v_cvt_pk_bf16_f32 v82, v84, v85
	v_cvt_pk_bf16_f32 v83, v86, v87
	s_nop 0
	s_waitcnt lgkmcnt(4)
	v_mfma_f32_32x32x16_bf16 v[48:63], v[216:219], v[80:83], v[48:63]
	v_exp_f32_e32 v88, v88
	v_exp_f32_e32 v89, v89
	v_exp_f32_e32 v90, v90
	v_mfma_f32_32x32x16_bf16 v[32:47], v[220:223], v[80:83], v[32:47]
	v_exp_f32_e32 v91, v91
	v_exp_f32_e32 v92, v92
	v_exp_f32_e32 v93, v93
	v_mfma_f32_32x32x16_bf16 v[16:31], v[224:227], v[80:83], v[16:31]
	v_exp_f32_e32 v94, v94
	v_exp_f32_e32 v95, v95
	v_add_f32_e32 v215, v88, v89
	v_add_f32_e32 v215, v215, v90
	v_mfma_f32_32x32x16_bf16 v[0:15], v[228:231], v[80:83], v[0:15]
	v_add_f32_e32 v215, v215, v91
	v_add_f32_e32 v215, v215, v92
	v_add_f32_e32 v215, v215, v93
	v_add_f32_e32 v215, v215, v94
	v_add_f32_e32 v215, v215, v95
	v_cvt_pk_bf16_f32 v84, v88, v89
	v_cvt_pk_bf16_f32 v85, v90, v91
	v_cvt_pk_bf16_f32 v86, v92, v93
	v_cvt_pk_bf16_f32 v87, v94, v95
	s_nop 0
	s_waitcnt lgkmcnt(0)
	v_mfma_f32_32x32x16_bf16 v[48:63], v[232:235], v[84:87], v[48:63]
	v_add_f32_e32 v183, v183, v185
	v_add_f32_e32 v187, v187, v215
	v_add_f32_e32 v183, v183, v187
	v_mov_b32_e32 v185, v183
	v_mfma_f32_32x32x16_bf16 v[32:47], v[236:239], v[84:87], v[32:47]
	v_mfma_f32_32x32x16_bf16 v[16:31], v[240:243], v[84:87], v[16:31]
	v_mfma_f32_32x32x16_bf16 v[0:15], v[244:247], v[84:87], v[0:15]
	s_nop 0
	s_nop 0
	v_permlane32_swap_b32_e32 v183, v185
	v_add_f32_e32 v183, v183, v185
	v_add_f32_e32 v189, v189, v183
	s_waitcnt vmcnt(6)
	s_barrier
	ds_read_b128 v[64:67], v191 offset:0
	ds_read_b128 v[68:71], v191 offset:4096
	s_add_u32 m0, s44, 0x6000
	ds_read_b128 v[72:75], v193 offset:0
	global_load_lds_dwordx4 v200, s[40:41]
	s_add_u32 m0, s44, 0x6400
	ds_read_b128 v[76:79], v193 offset:4096
	global_load_lds_dwordx4 v190, s[40:41]
	s_add_u32 m0, s45, 0x6000
	ds_read_b128 v[216:219], v195 offset:0
	global_load_lds_dwordx4 v192, s[42:43]
	s_add_u32 m0, s45, 0x6400
	ds_read_b128 v[220:223], v195 offset:4096
	global_load_lds_dwordx4 v194, s[42:43]
	s_add_u32 m0, s45, 0x6800
	ds_read_b128 v[224:227], v197 offset:0
	global_load_lds_dwordx4 v196, s[42:43]
	s_add_u32 m0, s45, 0x6c00
	ds_read_b128 v[228:231], v197 offset:4096
	global_load_lds_dwordx4 v198, s[42:43]
	s_add_u32 s40, s40, 0x18000
	s_addc_u32 s41, s41, 0
	s_add_u32 s42, s42, 0x80
	s_addc_u32 s43, s43, 0
	ds_read_b128 v[232:235], v191 offset:8192
	ds_read_b128 v[236:239], v191 offset:12288
	ds_read_b128 v[240:243], v191 offset:16384
	ds_read_b128 v[244:247], v191 offset:20480
	s_waitcnt lgkmcnt(11)
	v_mfma_f32_32x32x16_bf16 v[112:127], v[64:67], v[140:143], v[96:111]
	ds_read_b128 v[64:67], v193 offset:8192
	s_waitcnt lgkmcnt(11)
	v_mfma_f32_32x32x16_bf16 v[80:95], v[68:71], v[140:143], v[96:111]
	ds_read_b128 v[68:71], v193 offset:12288
	s_waitcnt lgkmcnt(11)
	v_mfma_f32_32x32x16_bf16 v[112:127], v[72:75], v[136:139], v[112:127]
	ds_read_b128 v[72:75], v193 offset:16384
	s_waitcnt lgkmcnt(11)
	v_mfma_f32_32x32x16_bf16 v[80:95], v[76:79], v[136:139], v[80:95]
	ds_read_b128 v[76:79], v193 offset:20480
	s_waitcnt lgkmcnt(11)
	v_mfma_f32_32x32x16_bf16 v[112:127], v[216:219], v[132:135], v[112:127]
	ds_read_b128 v[216:219], v195 offset:8192
	s_waitcnt lgkmcnt(11)
	v_mfma_f32_32x32x16_bf16 v[80:95], v[220:223], v[132:135], v[80:95]
	ds_read_b128 v[220:223], v195 offset:12288
	s_waitcnt lgkmcnt(11)
	v_mfma_f32_32x32x16_bf16 v[112:127], v[224:227], v[128:131], v[112:127]
	ds_read_b128 v[224:227], v195 offset:16384
	s_waitcnt lgkmcnt(11)
	v_mfma_f32_32x32x16_bf16 v[80:95], v[228:231], v[128:131], v[80:95]
	ds_read_b128 v[228:231], v195 offset:20480
	s_nop 7
	s_nop 3
	v_max3_f32 v175, v112, v113, v114
	v_max3_f32 v177, v115, v116, v117
	v_max3_f32 v179, v118, v119, v120
	v_max3_f32 v181, v121, v122, v123
	v_max3_f32 v248, v124, v125, v126
	v_max3_f32 v249, v127, v80, v81
	v_max3_f32 v250, v82, v83, v84
	v_max3_f32 v251, v85, v86, v87
	v_max3_f32 v253, v88, v89, v90
	v_max3_f32 v254, v91, v92, v93
	v_max_f32_e32 v255, v94, v95
	v_max3_f32 v175, v175, v177, v179
	v_max3_f32 v181, v181, v248, v249
	v_max3_f32 v250, v250, v251, v253
	v_max_f32_e32 v254, v254, v255
	v_max3_f32 v175, v175, v181, v250
	v_max_f32_e32 v175, v175, v254
	v_mov_b32_e32 v177, v175
	s_nop 1
	v_permlane32_swap_b32_e32 v175, v177
	v_max_f32_e32 v175, v175, v177
	v_cmp_lt_f32_e32 vcc, 0x41000000, v175
	s_cbranch_vccnz .Latt_resc_b

.Latt_noissue_c:
	ds_read_b128 v[232:235], v173 offset:8192
	ds_read_b128 v[236:239], v173 offset:12288
	ds_read_b128 v[240:243], v173 offset:16384
	ds_read_b128 v[244:247], v173 offset:20480
	s_waitcnt lgkmcnt(11)
	v_mfma_f32_32x32x16_bf16 v[112:127], v[64:67], v[140:143], v[96:111]
	ds_read_b128 v[64:67], v171 offset:8192
	s_waitcnt lgkmcnt(11)
	v_mfma_f32_32x32x16_bf16 v[80:95], v[68:71], v[140:143], v[96:111]
	ds_read_b128 v[68:71], v171 offset:12288
	s_waitcnt lgkmcnt(11)
	v_mfma_f32_32x32x16_bf16 v[112:127], v[72:75], v[136:139], v[112:127]
	ds_read_b128 v[72:75], v171 offset:16384
	s_waitcnt lgkmcnt(11)
	v_mfma_f32_32x32x16_bf16 v[80:95], v[76:79], v[136:139], v[80:95]
	ds_read_b128 v[76:79], v171 offset:20480
	s_waitcnt lgkmcnt(11)
	v_mfma_f32_32x32x16_bf16 v[112:127], v[216:219], v[132:135], v[112:127]
	ds_read_b128 v[216:219], v169 offset:8192
	s_waitcnt lgkmcnt(11)
	v_mfma_f32_32x32x16_bf16 v[80:95], v[220:223], v[132:135], v[80:95]
	ds_read_b128 v[220:223], v169 offset:12288
	s_waitcnt lgkmcnt(11)
	v_mfma_f32_32x32x16_bf16 v[112:127], v[224:227], v[128:131], v[112:127]
	ds_read_b128 v[224:227], v169 offset:16384
	s_waitcnt lgkmcnt(11)
	v_mfma_f32_32x32x16_bf16 v[80:95], v[228:231], v[128:131], v[80:95]
	ds_read_b128 v[228:231], v169 offset:20480
	s_nop 7
	s_nop 3
	v_max3_f32 v175, v112, v113, v114
	v_max3_f32 v177, v115, v116, v117
	v_max3_f32 v179, v118, v119, v120
	v_max3_f32 v181, v121, v122, v123
	v_max3_f32 v248, v124, v125, v126
	v_max3_f32 v249, v127, v80, v81
	v_max3_f32 v250, v82, v83, v84
	v_max3_f32 v251, v85, v86, v87
	v_max3_f32 v253, v88, v89, v90
	v_max3_f32 v254, v91, v92, v93
	v_max_f32_e32 v255, v94, v95
	v_max3_f32 v175, v175, v177, v179
	v_max3_f32 v181, v181, v248, v249
	v_max3_f32 v250, v250, v251, v253
	v_max_f32_e32 v254, v254, v255
	v_max3_f32 v175, v175, v181, v250
	v_max_f32_e32 v175, v175, v254
	v_mov_b32_e32 v177, v175
	s_nop 1
	v_permlane32_swap_b32_e32 v175, v177
	v_max_f32_e32 v175, v175, v177
	v_cmp_lt_f32_e32 vcc, 0x41000000, v175
	s_cbranch_vccnz .Latt_resc_c
.Latt_cont_c:
	v_exp_f32_e32 v112, v112
	v_exp_f32_e32 v113, v113
	v_exp_f32_e32 v114, v114
	v_exp_f32_e32 v115, v115
	v_exp_f32_e32 v116, v116
	v_exp_f32_e32 v117, v117
	v_exp_f32_e32 v118, v118
	v_exp_f32_e32 v119, v119
	v_add_f32_e32 v183, v112, v113
	v_add_f32_e32 v183, v183, v114
	v_add_f32_e32 v183, v183, v115
	v_add_f32_e32 v183, v183, v116
	v_add_f32_e32 v183, v183, v117
	v_add_f32_e32 v183, v183, v118
	v_add_f32_e32 v183, v183, v119
	v_cvt_pk_bf16_f32 v112, v112, v113
	v_cvt_pk_bf16_f32 v113, v114, v115
	v_cvt_pk_bf16_f32 v114, v116, v117
	v_cvt_pk_bf16_f32 v115, v118, v119
	v_exp_f32_e32 v120, v120
	v_exp_f32_e32 v121, v121
	s_waitcnt lgkmcnt(8)
	v_mfma_f32_32x32x16_bf16 v[48:63], v[232:235], v[112:115], v[48:63]
	v_exp_f32_e32 v122, v122
	v_exp_f32_e32 v123, v123
	v_exp_f32_e32 v124, v124
	v_mfma_f32_32x32x16_bf16 v[32:47], v[236:239], v[112:115], v[32:47]
	v_exp_f32_e32 v125, v125
	v_exp_f32_e32 v126, v126
	v_exp_f32_e32 v127, v127
	v_mfma_f32_32x32x16_bf16 v[16:31], v[240:243], v[112:115], v[16:31]
	v_add_f32_e32 v185, v120, v121
	v_add_f32_e32 v185, v185, v122
	v_add_f32_e32 v185, v185, v123
	v_add_f32_e32 v185, v185, v124
	v_add_f32_e32 v185, v185, v125
	v_add_f32_e32 v185, v185, v126
	v_mfma_f32_32x32x16_bf16 v[0:15], v[244:247], v[112:115], v[0:15]
	ds_read_b128 v[232:235], v167 offset:8192
	ds_read_b128 v[236:239], v167 offset:12288
	ds_read_b128 v[240:243], v167 offset:16384
	ds_read_b128 v[244:247], v167 offset:20480
	v_add_f32_e32 v185, v185, v127
	v_cvt_pk_bf16_f32 v116, v120, v121
	v_cvt_pk_bf16_f32 v117, v122, v123
	v_cvt_pk_bf16_f32 v118, v124, v125
	v_cvt_pk_bf16_f32 v119, v126, v127
	s_nop 0
	s_waitcnt lgkmcnt(8)
	v_mfma_f32_32x32x16_bf16 v[48:63], v[64:67], v[116:119], v[48:63]
	v_exp_f32_e32 v80, v80
	v_exp_f32_e32 v81, v81
	v_exp_f32_e32 v82, v82
	v_mfma_f32_32x32x16_bf16 v[32:47], v[68:71], v[116:119], v[32:47]
	v_exp_f32_e32 v83, v83
	v_exp_f32_e32 v84, v84
	v_exp_f32_e32 v85, v85
	v_mfma_f32_32x32x16_bf16 v[16:31], v[72:75], v[116:119], v[16:31]
	v_exp_f32_e32 v86, v86
	v_exp_f32_e32 v87, v87
	v_add_f32_e32 v187, v80, v81
	v_add_f32_e32 v187, v187, v82
	v_mfma_f32_32x32x16_bf16 v[0:15], v[76:79], v[116:119], v[0:15]
	v_add_f32_e32 v187, v187, v83
	v_add_f32_e32 v187, v187, v84
	v_add_f32_e32 v187, v187, v85
	v_add_f32_e32 v187, v187, v86
	v_add_f32_e32 v187, v187, v87
	v_cvt_pk_bf16_f32 v80, v80, v81
	v_cvt_pk_bf16_f32 v81, v82, v83
	v_cvt_pk_bf16_f32 v82, v84, v85
	v_cvt_pk_bf16_f32 v83, v86, v87
	s_nop 0
	s_waitcnt lgkmcnt(4)
	v_mfma_f32_32x32x16_bf16 v[48:63], v[216:219], v[80:83], v[48:63]
	v_exp_f32_e32 v88, v88
	v_exp_f32_e32 v89, v89
	v_exp_f32_e32 v90, v90
	v_mfma_f32_32x32x16_bf16 v[32:47], v[220:223], v[80:83], v[32:47]
	v_exp_f32_e32 v91, v91
	v_exp_f32_e32 v92, v92
	v_exp_f32_e32 v93, v93
	v_mfma_f32_32x32x16_bf16 v[16:31], v[224:227], v[80:83], v[16:31]
	v_exp_f32_e32 v94, v94
	v_exp_f32_e32 v95, v95
	v_add_f32_e32 v215, v88, v89
	v_add_f32_e32 v215, v215, v90
	v_mfma_f32_32x32x16_bf16 v[0:15], v[228:231], v[80:83], v[0:15]
	v_add_f32_e32 v215, v215, v91
	v_add_f32_e32 v215, v215, v92
	v_add_f32_e32 v215, v215, v93
	v_add_f32_e32 v215, v215, v94
	v_add_f32_e32 v215, v215, v95
	v_cvt_pk_bf16_f32 v84, v88, v89
	v_cvt_pk_bf16_f32 v85, v90, v91
	v_cvt_pk_bf16_f32 v86, v92, v93
	v_cvt_pk_bf16_f32 v87, v94, v95
	s_nop 0
	s_waitcnt lgkmcnt(0)
	v_mfma_f32_32x32x16_bf16 v[48:63], v[232:235], v[84:87], v[48:63]
	v_add_f32_e32 v183, v183, v185
	v_add_f32_e32 v187, v187, v215
	v_add_f32_e32 v183, v183, v187
	v_mov_b32_e32 v185, v183
	v_mfma_f32_32x32x16_bf16 v[32:47], v[236:239], v[84:87], v[32:47]
	v_mfma_f32_32x32x16_bf16 v[16:31], v[240:243], v[84:87], v[16:31]
	v_mfma_f32_32x32x16_bf16 v[0:15], v[244:247], v[84:87], v[0:15]
	s_nop 0
	s_nop 0
	v_permlane32_swap_b32_e32 v183, v185
	v_add_f32_e32 v183, v183, v185
	v_add_f32_e32 v189, v189, v183
	s_sub_u32 s46, s46, 1
	s_cmp_lg_u32 s46, 0
	s_cbranch_scc1 .Latt_loop
	s_waitcnt vmcnt(0)
	s_barrier
	ds_read_b128 v[64:67], v173 offset:24576
	ds_read_b128 v[68:71], v173 offset:28672
	ds_read_b128 v[72:75], v171 offset:24576
	ds_read_b128 v[76:79], v171 offset:28672
	ds_read_b128 v[216:219], v169 offset:24576
	ds_read_b128 v[220:223], v169 offset:28672
	ds_read_b128 v[224:227], v167 offset:24576
	ds_read_b128 v[228:231], v167 offset:28672
	ds_read_b128 v[232:235], v173 offset:32768
	ds_read_b128 v[236:239], v173 offset:36864
	ds_read_b128 v[240:243], v173 offset:40960
	ds_read_b128 v[244:247], v173 offset:45056
	s_waitcnt lgkmcnt(11)
	v_mfma_f32_32x32x16_bf16 v[112:127], v[64:67], v[140:143], v[96:111]
	ds_read_b128 v[64:67], v171 offset:32768
	s_waitcnt lgkmcnt(11)
	v_mfma_f32_32x32x16_bf16 v[80:95], v[68:71], v[140:143], v[96:111]
	ds_read_b128 v[68:71], v171 offset:36864
	s_waitcnt lgkmcnt(11)
	v_mfma_f32_32x32x16_bf16 v[112:127], v[72:75], v[136:139], v[112:127]
	ds_read_b128 v[72:75], v171 offset:40960
	s_waitcnt lgkmcnt(11)
	v_mfma_f32_32x32x16_bf16 v[80:95], v[76:79], v[136:139], v[80:95]
	ds_read_b128 v[76:79], v171 offset:45056
	s_waitcnt lgkmcnt(11)
	v_mfma_f32_32x32x16_bf16 v[112:127], v[216:219], v[132:135], v[112:127]
	ds_read_b128 v[216:219], v169 offset:32768
	s_waitcnt lgkmcnt(11)
	v_mfma_f32_32x32x16_bf16 v[80:95], v[220:223], v[132:135], v[80:95]
	ds_read_b128 v[220:223], v169 offset:36864
	s_waitcnt lgkmcnt(11)
	v_mfma_f32_32x32x16_bf16 v[112:127], v[224:227], v[128:131], v[112:127]
	ds_read_b128 v[224:227], v169 offset:40960
	s_waitcnt lgkmcnt(11)
	v_mfma_f32_32x32x16_bf16 v[80:95], v[228:231], v[128:131], v[80:95]
	ds_read_b128 v[228:231], v169 offset:45056
	s_nop 7
	s_nop 3
	v_max3_f32 v175, v112, v113, v114
	v_max3_f32 v177, v115, v116, v117
	v_max3_f32 v179, v118, v119, v120
	v_max3_f32 v181, v121, v122, v123
	v_max3_f32 v248, v124, v125, v126
	v_max3_f32 v249, v127, v80, v81
	v_max3_f32 v250, v82, v83, v84
	v_max3_f32 v251, v85, v86, v87
	v_max3_f32 v253, v88, v89, v90
	v_max3_f32 v254, v91, v92, v93
	v_max_f32_e32 v255, v94, v95
	v_max3_f32 v175, v175, v177, v179
	v_max3_f32 v181, v181, v248, v249
	v_max3_f32 v250, v250, v251, v253
	v_max_f32_e32 v254, v254, v255
	v_max3_f32 v175, v175, v181, v250
	v_max_f32_e32 v175, v175, v254
	v_mov_b32_e32 v177, v175
	s_nop 1
	v_permlane32_swap_b32_e32 v175, v177
	v_max_f32_e32 v175, v175, v177
	v_cmp_lt_f32_e32 vcc, 0x41000000, v175
	s_cbranch_vccnz .Latt_resc_t
